# pool-layer row phase: trailing-window row loads issued as one masked batch instead of a serial load-wait loop (main path)
# speedup vs baseline: 1.0406x; 1.0082x over previous
; __device__ __forceinline__ void unpack8(const u32x4 w, float* v) { v[0] = bflo(w.x); v[1] = bfhi(w.x); v[2] = bflo(w.y); v[3] = bfhi(w.y); v[4] = bflo(w.z); v[5] = bfhi(w.z); v[6] = bflo(w.w); v[7] = bfhi(w.w); }
; __device__ __forceinline__ void row_res(KP kp, int gpost_in, int layer, bool has_next, int wid0, int row0, int row1, int b0, int nb, int tailp, bool pooled) {
;     ...
;                 else if (pooled) { const int t = row % LL, win = 2 << (c * 2 + (lane >> 5)), cnt = (t + 1) < win ? (t + 1) : win; const bf16* zp = MX + (size_t)row * DM + c * 512 + lane * 8;
;                     float z0[8], sum[8]; unpack8(*(const u32x4*)zp, z0);
; #pragma unroll
;                     for (int j = 0; j < 8; ++j) sum[j] = z0[j];
;                     for (int d = 1; d < cnt; ++d) { float zd[8]; unpack8(*(const u32x4*)(zp - (size_t)d * DM), zd);
; #pragma unroll
;                         for (int j = 0; j < 8; ++j) sum[j] += zd[j]; }
;                     const float inv = 1.0f / (float)cnt;
; #pragma unroll
;                     for (int j = 0; j < 8; ++j) m[r][c][j] = sum[j] * inv - z0[j]; }
.LBB0_780:
	v_mul_hi_i32 v6, v38, s62
	v_lshrrev_b32_e32 v7, 31, v6
	v_ashrrev_i32_e32 v6, 7, v6
	v_add_u32_e32 v58, v6, v7
	v_mul_i32_i24_e32 v6, 0x810, v58
	v_sub_u32_e32 v6, v38, v6
	s_andn2_b64 vcc, exec, s[4:5]
	v_add_u32_e32 v16, 1, v6
	s_cbranch_vccnz .LBB0_786
	v_min_i32_e32 v17, v16, v1
	v_cmp_lt_i32_e32 vcc, 1, v17
	v_mov_b64_e32 v[12:13], v[22:23]
	v_mov_b64_e32 v[10:11], v[24:25]
	v_mov_b64_e32 v[8:9], v[26:27]
	v_mov_b64_e32 v[6:7], v[28:29]
	s_and_saveexec_b64 s[4:5], vcc
	s_cbranch_execz .LBB0_785
	v_add_u32_e32 v18, -1, v17
	s_mov_b64 s[14:15], 0
	v_mov_b64_e32 v[14:15], v[48:49]
	v_mov_b64_e32 v[6:7], v[28:29]
	v_mov_b64_e32 v[8:9], v[26:27]
	v_mov_b64_e32 v[10:11], v[24:25]
	v_mov_b64_e32 v[12:13], v[22:23]
	s_mov_b64 s[14:15], exec
	global_load_dwordx4 v[174:177], v[14:15], off
	v_lshl_add_u64 v[14:15], v[14:15], 0, s[54:55]
	v_cmp_le_u32_e32 vcc, 2, v18
	s_and_b64 exec, s[14:15], vcc
	s_cbranch_execz .Lpl_a_iss
	global_load_dwordx4 v[178:181], v[14:15], off
	v_lshl_add_u64 v[14:15], v[14:15], 0, s[54:55]
	v_cmp_le_u32_e32 vcc, 3, v18
	s_and_b64 exec, s[14:15], vcc
	s_cbranch_execz .Lpl_a_iss
	global_load_dwordx4 v[182:185], v[14:15], off
.Lpl_a_iss:
	s_mov_b64 exec, s[14:15]
	s_waitcnt vmcnt(0)
	v_lshlrev_b32_e32 v234, 16, v174
	v_and_b32_e32 v235, 0xffff0000, v174
	v_pk_add_f32 v[12:13], v[12:13], v[234:235]
	v_lshlrev_b32_e32 v234, 16, v175
	v_and_b32_e32 v235, 0xffff0000, v175
	v_pk_add_f32 v[10:11], v[10:11], v[234:235]
	v_lshlrev_b32_e32 v234, 16, v176
	v_and_b32_e32 v235, 0xffff0000, v176
	v_pk_add_f32 v[8:9], v[8:9], v[234:235]
	v_lshlrev_b32_e32 v234, 16, v177
	v_and_b32_e32 v235, 0xffff0000, v177
	v_pk_add_f32 v[6:7], v[6:7], v[234:235]
	v_cmp_le_u32_e32 vcc, 2, v18
	s_and_b64 exec, s[14:15], vcc
	s_cbranch_execz .Lpl_a_done
	v_lshlrev_b32_e32 v234, 16, v178
	v_and_b32_e32 v235, 0xffff0000, v178
	v_pk_add_f32 v[12:13], v[12:13], v[234:235]
	v_lshlrev_b32_e32 v234, 16, v179
	v_and_b32_e32 v235, 0xffff0000, v179
	v_pk_add_f32 v[10:11], v[10:11], v[234:235]
	v_lshlrev_b32_e32 v234, 16, v180
	v_and_b32_e32 v235, 0xffff0000, v180
	v_pk_add_f32 v[8:9], v[8:9], v[234:235]
	v_lshlrev_b32_e32 v234, 16, v181
	v_and_b32_e32 v235, 0xffff0000, v181
	v_pk_add_f32 v[6:7], v[6:7], v[234:235]
	v_cmp_le_u32_e32 vcc, 3, v18
	s_and_b64 exec, s[14:15], vcc
	s_cbranch_execz .Lpl_a_done
	v_lshlrev_b32_e32 v234, 16, v182
	v_and_b32_e32 v235, 0xffff0000, v182
	v_pk_add_f32 v[12:13], v[12:13], v[234:235]
	v_lshlrev_b32_e32 v234, 16, v183
	v_and_b32_e32 v235, 0xffff0000, v183
	v_pk_add_f32 v[10:11], v[10:11], v[234:235]
	v_lshlrev_b32_e32 v234, 16, v184
	v_and_b32_e32 v235, 0xffff0000, v184
	v_pk_add_f32 v[8:9], v[8:9], v[234:235]
	v_lshlrev_b32_e32 v234, 16, v185
	v_and_b32_e32 v235, 0xffff0000, v185
	v_pk_add_f32 v[6:7], v[6:7], v[234:235]
.Lpl_a_done:
	s_mov_b64 exec, s[14:15]

; __device__ __forceinline__ void unpack8(const u32x4 w, float* v) { v[0] = bflo(w.x); v[1] = bfhi(w.x); v[2] = bflo(w.y); v[3] = bfhi(w.y); v[4] = bflo(w.z); v[5] = bfhi(w.z); v[6] = bflo(w.w); v[7] = bfhi(w.w); }
; __device__ __forceinline__ void row_res(KP kp, int gpost_in, int layer, bool has_next, int wid0, int row0, int row1, int b0, int nb, int tailp, bool pooled) {
;     ...
;                 else if (pooled) { const int t = row % LL, win = 2 << (c * 2 + (lane >> 5)), cnt = (t + 1) < win ? (t + 1) : win; const bf16* zp = MX + (size_t)row * DM + c * 512 + lane * 8;
;                     float z0[8], sum[8]; unpack8(*(const u32x4*)zp, z0);
; #pragma unroll
;                     for (int j = 0; j < 8; ++j) sum[j] = z0[j];
;                     for (int d = 1; d < cnt; ++d) { float zd[8]; unpack8(*(const u32x4*)(zp - (size_t)d * DM), zd);
; #pragma unroll
;                         for (int j = 0; j < 8; ++j) sum[j] += zd[j]; }
;                     const float inv = 1.0f / (float)cnt;
; #pragma unroll
;                     for (int j = 0; j < 8; ++j) m[r][c][j] = sum[j] * inv - z0[j]; }
.LBB0_788:
	s_andn2_b64 vcc, exec, s[14:15]
	s_cbranch_vccnz .LBB0_794
	v_min_i32_e32 v16, v16, v41
	v_cmp_lt_i32_e32 vcc, 1, v16
	v_mov_b64_e32 v[12:13], v[30:31]
	v_mov_b64_e32 v[10:11], v[32:33]
	v_mov_b64_e32 v[8:9], v[34:35]
	v_mov_b64_e32 v[6:7], v[36:37]
	s_and_saveexec_b64 s[14:15], vcc
	s_cbranch_execz .LBB0_793
	v_add_u32_e32 v17, -1, v16
	s_mov_b64 s[40:41], 0
	v_mov_b64_e32 v[14:15], v[50:51]
	v_mov_b64_e32 v[6:7], v[36:37]
	v_mov_b64_e32 v[8:9], v[34:35]
	v_mov_b64_e32 v[10:11], v[32:33]
	v_mov_b64_e32 v[12:13], v[30:31]
	s_mov_b64 s[40:41], exec
	global_load_dwordx4 v[174:177], v[14:15], off
	v_lshl_add_u64 v[14:15], v[14:15], 0, s[54:55]
	v_cmp_le_u32_e32 vcc, 2, v17
	s_and_b64 exec, s[40:41], vcc
	s_cbranch_execz .Lpl_b_iss
	global_load_dwordx4 v[178:181], v[14:15], off
	v_lshl_add_u64 v[14:15], v[14:15], 0, s[54:55]
	v_cmp_le_u32_e32 vcc, 3, v17
	s_and_b64 exec, s[40:41], vcc
	s_cbranch_execz .Lpl_b_iss
	global_load_dwordx4 v[182:185], v[14:15], off
	v_lshl_add_u64 v[14:15], v[14:15], 0, s[54:55]
	v_cmp_le_u32_e32 vcc, 4, v17
	s_and_b64 exec, s[40:41], vcc
	s_cbranch_execz .Lpl_b_iss
	global_load_dwordx4 v[186:189], v[14:15], off
	v_lshl_add_u64 v[14:15], v[14:15], 0, s[54:55]
	v_cmp_le_u32_e32 vcc, 5, v17
	s_and_b64 exec, s[40:41], vcc
	s_cbranch_execz .Lpl_b_iss
	global_load_dwordx4 v[190:193], v[14:15], off
	v_lshl_add_u64 v[14:15], v[14:15], 0, s[54:55]
	v_cmp_le_u32_e32 vcc, 6, v17
	s_and_b64 exec, s[40:41], vcc
	s_cbranch_execz .Lpl_b_iss
	global_load_dwordx4 v[194:197], v[14:15], off
	v_lshl_add_u64 v[14:15], v[14:15], 0, s[54:55]
	v_cmp_le_u32_e32 vcc, 7, v17
	s_and_b64 exec, s[40:41], vcc
	s_cbranch_execz .Lpl_b_iss
	global_load_dwordx4 v[198:201], v[14:15], off
	v_lshl_add_u64 v[14:15], v[14:15], 0, s[54:55]
	v_cmp_le_u32_e32 vcc, 8, v17
	s_and_b64 exec, s[40:41], vcc
	s_cbranch_execz .Lpl_b_iss
	global_load_dwordx4 v[202:205], v[14:15], off
	v_lshl_add_u64 v[14:15], v[14:15], 0, s[54:55]
	v_cmp_le_u32_e32 vcc, 9, v17
	s_and_b64 exec, s[40:41], vcc
	s_cbranch_execz .Lpl_b_iss
	global_load_dwordx4 v[206:209], v[14:15], off
	v_lshl_add_u64 v[14:15], v[14:15], 0, s[54:55]
	v_cmp_le_u32_e32 vcc, 10, v17
	s_and_b64 exec, s[40:41], vcc
	s_cbranch_execz .Lpl_b_iss
	global_load_dwordx4 v[210:213], v[14:15], off
	v_lshl_add_u64 v[14:15], v[14:15], 0, s[54:55]
	v_cmp_le_u32_e32 vcc, 11, v17
	s_and_b64 exec, s[40:41], vcc
	s_cbranch_execz .Lpl_b_iss
	global_load_dwordx4 v[214:217], v[14:15], off
	v_lshl_add_u64 v[14:15], v[14:15], 0, s[54:55]
	v_cmp_le_u32_e32 vcc, 12, v17
	s_and_b64 exec, s[40:41], vcc
	s_cbranch_execz .Lpl_b_iss
	global_load_dwordx4 v[218:221], v[14:15], off
	v_lshl_add_u64 v[14:15], v[14:15], 0, s[54:55]
	v_cmp_le_u32_e32 vcc, 13, v17
	s_and_b64 exec, s[40:41], vcc
	s_cbranch_execz .Lpl_b_iss
	global_load_dwordx4 v[222:225], v[14:15], off
	v_lshl_add_u64 v[14:15], v[14:15], 0, s[54:55]
	v_cmp_le_u32_e32 vcc, 14, v17
	s_and_b64 exec, s[40:41], vcc
	s_cbranch_execz .Lpl_b_iss
	global_load_dwordx4 v[226:229], v[14:15], off
	v_lshl_add_u64 v[14:15], v[14:15], 0, s[54:55]
	v_cmp_le_u32_e32 vcc, 15, v17
	s_and_b64 exec, s[40:41], vcc
	s_cbranch_execz .Lpl_b_iss
	global_load_dwordx4 v[230:233], v[14:15], off
.Lpl_b_iss:
	s_mov_b64 exec, s[40:41]
	s_waitcnt vmcnt(0)
	v_lshlrev_b32_e32 v234, 16, v174
	v_and_b32_e32 v235, 0xffff0000, v174
	v_pk_add_f32 v[12:13], v[12:13], v[234:235]
	v_lshlrev_b32_e32 v234, 16, v175
	v_and_b32_e32 v235, 0xffff0000, v175
	v_pk_add_f32 v[10:11], v[10:11], v[234:235]
	v_lshlrev_b32_e32 v234, 16, v176
	v_and_b32_e32 v235, 0xffff0000, v176
	v_pk_add_f32 v[8:9], v[8:9], v[234:235]
	v_lshlrev_b32_e32 v234, 16, v177
	v_and_b32_e32 v235, 0xffff0000, v177
	v_pk_add_f32 v[6:7], v[6:7], v[234:235]
	v_cmp_le_u32_e32 vcc, 2, v17
	s_and_b64 exec, s[40:41], vcc
	s_cbranch_execz .Lpl_b_done
	v_lshlrev_b32_e32 v234, 16, v178
	v_and_b32_e32 v235, 0xffff0000, v178
	v_pk_add_f32 v[12:13], v[12:13], v[234:235]
	v_lshlrev_b32_e32 v234, 16, v179
	v_and_b32_e32 v235, 0xffff0000, v179
	v_pk_add_f32 v[10:11], v[10:11], v[234:235]
	v_lshlrev_b32_e32 v234, 16, v180
	v_and_b32_e32 v235, 0xffff0000, v180
	v_pk_add_f32 v[8:9], v[8:9], v[234:235]
	v_lshlrev_b32_e32 v234, 16, v181
	v_and_b32_e32 v235, 0xffff0000, v181
	v_pk_add_f32 v[6:7], v[6:7], v[234:235]
	v_cmp_le_u32_e32 vcc, 3, v17
	s_and_b64 exec, s[40:41], vcc
	s_cbranch_execz .Lpl_b_done
	v_lshlrev_b32_e32 v234, 16, v182
	v_and_b32_e32 v235, 0xffff0000, v182
	v_pk_add_f32 v[12:13], v[12:13], v[234:235]
	v_lshlrev_b32_e32 v234, 16, v183
	v_and_b32_e32 v235, 0xffff0000, v183
	v_pk_add_f32 v[10:11], v[10:11], v[234:235]
	v_lshlrev_b32_e32 v234, 16, v184
	v_and_b32_e32 v235, 0xffff0000, v184
	v_pk_add_f32 v[8:9], v[8:9], v[234:235]
	v_lshlrev_b32_e32 v234, 16, v185
	v_and_b32_e32 v235, 0xffff0000, v185
	v_pk_add_f32 v[6:7], v[6:7], v[234:235]
	v_cmp_le_u32_e32 vcc, 4, v17
	s_and_b64 exec, s[40:41], vcc
	s_cbranch_execz .Lpl_b_done
	v_lshlrev_b32_e32 v234, 16, v186
	v_and_b32_e32 v235, 0xffff0000, v186
	v_pk_add_f32 v[12:13], v[12:13], v[234:235]
	v_lshlrev_b32_e32 v234, 16, v187
	v_and_b32_e32 v235, 0xffff0000, v187
	v_pk_add_f32 v[10:11], v[10:11], v[234:235]
	v_lshlrev_b32_e32 v234, 16, v188
	v_and_b32_e32 v235, 0xffff0000, v188
	v_pk_add_f32 v[8:9], v[8:9], v[234:235]
	v_lshlrev_b32_e32 v234, 16, v189
	v_and_b32_e32 v235, 0xffff0000, v189
	v_pk_add_f32 v[6:7], v[6:7], v[234:235]
	v_cmp_le_u32_e32 vcc, 5, v17
	s_and_b64 exec, s[40:41], vcc
	s_cbranch_execz .Lpl_b_done
; __device__ __forceinline__ void unpack8(const u32x4 w, float* v) { v[0] = bflo(w.x); v[1] = bfhi(w.x); v[2] = bflo(w.y); v[3] = bfhi(w.y); v[4] = bflo(w.z); v[5] = bfhi(w.z); v[6] = bflo(w.w); v[7] = bfhi(w.w); }
; __device__ __forceinline__ void row_res(KP kp, int gpost_in, int layer, bool has_next, int wid0, int row0, int row1, int b0, int nb, int tailp, bool pooled) {
;     ...
;                 else if (pooled) { const int t = row % LL, win = 2 << (c * 2 + (lane >> 5)), cnt = (t + 1) < win ? (t + 1) : win; const bf16* zp = MX + (size_t)row * DM + c * 512 + lane * 8;
;                     float z0[8], sum[8]; unpack8(*(const u32x4*)zp, z0);
; #pragma unroll
;                     for (int j = 0; j < 8; ++j) sum[j] = z0[j];
;                     for (int d = 1; d < cnt; ++d) { float zd[8]; unpack8(*(const u32x4*)(zp - (size_t)d * DM), zd);
; #pragma unroll
;                         for (int j = 0; j < 8; ++j) sum[j] += zd[j]; }
;                     const float inv = 1.0f / (float)cnt;
; #pragma unroll
;                     for (int j = 0; j < 8; ++j) m[r][c][j] = sum[j] * inv - z0[j]; }
	v_lshlrev_b32_e32 v234, 16, v190
	v_and_b32_e32 v235, 0xffff0000, v190
	v_pk_add_f32 v[12:13], v[12:13], v[234:235]
	v_lshlrev_b32_e32 v234, 16, v191
	v_and_b32_e32 v235, 0xffff0000, v191
	v_pk_add_f32 v[10:11], v[10:11], v[234:235]
	v_lshlrev_b32_e32 v234, 16, v192
	v_and_b32_e32 v235, 0xffff0000, v192
	v_pk_add_f32 v[8:9], v[8:9], v[234:235]
	v_lshlrev_b32_e32 v234, 16, v193
	v_and_b32_e32 v235, 0xffff0000, v193
	v_pk_add_f32 v[6:7], v[6:7], v[234:235]
	v_cmp_le_u32_e32 vcc, 6, v17
	s_and_b64 exec, s[40:41], vcc
	s_cbranch_execz .Lpl_b_done
	v_lshlrev_b32_e32 v234, 16, v194
	v_and_b32_e32 v235, 0xffff0000, v194
	v_pk_add_f32 v[12:13], v[12:13], v[234:235]
	v_lshlrev_b32_e32 v234, 16, v195
	v_and_b32_e32 v235, 0xffff0000, v195
	v_pk_add_f32 v[10:11], v[10:11], v[234:235]
	v_lshlrev_b32_e32 v234, 16, v196
	v_and_b32_e32 v235, 0xffff0000, v196
	v_pk_add_f32 v[8:9], v[8:9], v[234:235]
	v_lshlrev_b32_e32 v234, 16, v197
	v_and_b32_e32 v235, 0xffff0000, v197
	v_pk_add_f32 v[6:7], v[6:7], v[234:235]
	v_cmp_le_u32_e32 vcc, 7, v17
	s_and_b64 exec, s[40:41], vcc
	s_cbranch_execz .Lpl_b_done
	v_lshlrev_b32_e32 v234, 16, v198
	v_and_b32_e32 v235, 0xffff0000, v198
	v_pk_add_f32 v[12:13], v[12:13], v[234:235]
	v_lshlrev_b32_e32 v234, 16, v199
	v_and_b32_e32 v235, 0xffff0000, v199
	v_pk_add_f32 v[10:11], v[10:11], v[234:235]
	v_lshlrev_b32_e32 v234, 16, v200
	v_and_b32_e32 v235, 0xffff0000, v200
	v_pk_add_f32 v[8:9], v[8:9], v[234:235]
	v_lshlrev_b32_e32 v234, 16, v201
	v_and_b32_e32 v235, 0xffff0000, v201
	v_pk_add_f32 v[6:7], v[6:7], v[234:235]
	v_cmp_le_u32_e32 vcc, 8, v17
	s_and_b64 exec, s[40:41], vcc
	s_cbranch_execz .Lpl_b_done
	v_lshlrev_b32_e32 v234, 16, v202
	v_and_b32_e32 v235, 0xffff0000, v202
	v_pk_add_f32 v[12:13], v[12:13], v[234:235]
	v_lshlrev_b32_e32 v234, 16, v203
	v_and_b32_e32 v235, 0xffff0000, v203
	v_pk_add_f32 v[10:11], v[10:11], v[234:235]
	v_lshlrev_b32_e32 v234, 16, v204
	v_and_b32_e32 v235, 0xffff0000, v204
	v_pk_add_f32 v[8:9], v[8:9], v[234:235]
	v_lshlrev_b32_e32 v234, 16, v205
	v_and_b32_e32 v235, 0xffff0000, v205
	v_pk_add_f32 v[6:7], v[6:7], v[234:235]
	v_cmp_le_u32_e32 vcc, 9, v17
	s_and_b64 exec, s[40:41], vcc
	s_cbranch_execz .Lpl_b_done
	v_lshlrev_b32_e32 v234, 16, v206
	v_and_b32_e32 v235, 0xffff0000, v206
	v_pk_add_f32 v[12:13], v[12:13], v[234:235]
	v_lshlrev_b32_e32 v234, 16, v207
	v_and_b32_e32 v235, 0xffff0000, v207
	v_pk_add_f32 v[10:11], v[10:11], v[234:235]
	v_lshlrev_b32_e32 v234, 16, v208
	v_and_b32_e32 v235, 0xffff0000, v208
	v_pk_add_f32 v[8:9], v[8:9], v[234:235]
	v_lshlrev_b32_e32 v234, 16, v209
	v_and_b32_e32 v235, 0xffff0000, v209
	v_pk_add_f32 v[6:7], v[6:7], v[234:235]
	v_cmp_le_u32_e32 vcc, 10, v17
	s_and_b64 exec, s[40:41], vcc
	s_cbranch_execz .Lpl_b_done
	v_lshlrev_b32_e32 v234, 16, v210
	v_and_b32_e32 v235, 0xffff0000, v210
	v_pk_add_f32 v[12:13], v[12:13], v[234:235]
	v_lshlrev_b32_e32 v234, 16, v211
	v_and_b32_e32 v235, 0xffff0000, v211
	v_pk_add_f32 v[10:11], v[10:11], v[234:235]
	v_lshlrev_b32_e32 v234, 16, v212
	v_and_b32_e32 v235, 0xffff0000, v212
	v_pk_add_f32 v[8:9], v[8:9], v[234:235]
	v_lshlrev_b32_e32 v234, 16, v213
	v_and_b32_e32 v235, 0xffff0000, v213
	v_pk_add_f32 v[6:7], v[6:7], v[234:235]
	v_cmp_le_u32_e32 vcc, 11, v17
	s_and_b64 exec, s[40:41], vcc
	s_cbranch_execz .Lpl_b_done
	v_lshlrev_b32_e32 v234, 16, v214
	v_and_b32_e32 v235, 0xffff0000, v214
	v_pk_add_f32 v[12:13], v[12:13], v[234:235]
	v_lshlrev_b32_e32 v234, 16, v215
	v_and_b32_e32 v235, 0xffff0000, v215
	v_pk_add_f32 v[10:11], v[10:11], v[234:235]
	v_lshlrev_b32_e32 v234, 16, v216
	v_and_b32_e32 v235, 0xffff0000, v216
	v_pk_add_f32 v[8:9], v[8:9], v[234:235]
	v_lshlrev_b32_e32 v234, 16, v217
	v_and_b32_e32 v235, 0xffff0000, v217
	v_pk_add_f32 v[6:7], v[6:7], v[234:235]
	v_cmp_le_u32_e32 vcc, 12, v17
	s_and_b64 exec, s[40:41], vcc
	s_cbranch_execz .Lpl_b_done
	v_lshlrev_b32_e32 v234, 16, v218
	v_and_b32_e32 v235, 0xffff0000, v218
	v_pk_add_f32 v[12:13], v[12:13], v[234:235]
	v_lshlrev_b32_e32 v234, 16, v219
	v_and_b32_e32 v235, 0xffff0000, v219
	v_pk_add_f32 v[10:11], v[10:11], v[234:235]
	v_lshlrev_b32_e32 v234, 16, v220
	v_and_b32_e32 v235, 0xffff0000, v220
	v_pk_add_f32 v[8:9], v[8:9], v[234:235]
	v_lshlrev_b32_e32 v234, 16, v221
	v_and_b32_e32 v235, 0xffff0000, v221
	v_pk_add_f32 v[6:7], v[6:7], v[234:235]
	v_cmp_le_u32_e32 vcc, 13, v17
	s_and_b64 exec, s[40:41], vcc
	s_cbranch_execz .Lpl_b_done
	v_lshlrev_b32_e32 v234, 16, v222
	v_and_b32_e32 v235, 0xffff0000, v222
	v_pk_add_f32 v[12:13], v[12:13], v[234:235]
	v_lshlrev_b32_e32 v234, 16, v223
	v_and_b32_e32 v235, 0xffff0000, v223
	v_pk_add_f32 v[10:11], v[10:11], v[234:235]
	v_lshlrev_b32_e32 v234, 16, v224
	v_and_b32_e32 v235, 0xffff0000, v224
	v_pk_add_f32 v[8:9], v[8:9], v[234:235]
	v_lshlrev_b32_e32 v234, 16, v225
	v_and_b32_e32 v235, 0xffff0000, v225
	v_pk_add_f32 v[6:7], v[6:7], v[234:235]
	v_cmp_le_u32_e32 vcc, 14, v17
	s_and_b64 exec, s[40:41], vcc
	s_cbranch_execz .Lpl_b_done
	v_lshlrev_b32_e32 v234, 16, v226
	v_and_b32_e32 v235, 0xffff0000, v226
	v_pk_add_f32 v[12:13], v[12:13], v[234:235]
	v_lshlrev_b32_e32 v234, 16, v227
	v_and_b32_e32 v235, 0xffff0000, v227
	v_pk_add_f32 v[10:11], v[10:11], v[234:235]
	v_lshlrev_b32_e32 v234, 16, v228
	v_and_b32_e32 v235, 0xffff0000, v228
	v_pk_add_f32 v[8:9], v[8:9], v[234:235]
	v_lshlrev_b32_e32 v234, 16, v229
	v_and_b32_e32 v235, 0xffff0000, v229
	v_pk_add_f32 v[6:7], v[6:7], v[234:235]
	v_cmp_le_u32_e32 vcc, 15, v17
	s_and_b64 exec, s[40:41], vcc
	s_cbranch_execz .Lpl_b_done
	v_lshlrev_b32_e32 v234, 16, v230
	v_and_b32_e32 v235, 0xffff0000, v230
	v_pk_add_f32 v[12:13], v[12:13], v[234:235]
	v_lshlrev_b32_e32 v234, 16, v231
	v_and_b32_e32 v235, 0xffff0000, v231
	v_pk_add_f32 v[10:11], v[10:11], v[234:235]
	v_lshlrev_b32_e32 v234, 16, v232
	v_and_b32_e32 v235, 0xffff0000, v232
	v_pk_add_f32 v[8:9], v[8:9], v[234:235]
	v_lshlrev_b32_e32 v234, 16, v233
	v_and_b32_e32 v235, 0xffff0000, v233
	v_pk_add_f32 v[6:7], v[6:7], v[234:235]
.Lpl_b_done:
	s_mov_b64 exec, s[40:41]

; __device__ __forceinline__ void unpack8(const u32x4 w, float* v) { v[0] = bflo(w.x); v[1] = bfhi(w.x); v[2] = bflo(w.y); v[3] = bfhi(w.y); v[4] = bflo(w.z); v[5] = bfhi(w.z); v[6] = bflo(w.w); v[7] = bfhi(w.w); }
; __device__ __forceinline__ void row_res(KP kp, int gpost_in, int layer, bool has_next, int wid0, int row0, int row1, int b0, int nb, int tailp, bool pooled) {
;     ...
;                 else if (pooled) { const int t = row % LL, win = 2 << (c * 2 + (lane >> 5)), cnt = (t + 1) < win ? (t + 1) : win; const bf16* zp = MX + (size_t)row * DM + c * 512 + lane * 8;
;                     float z0[8], sum[8]; unpack8(*(const u32x4*)zp, z0);
; #pragma unroll
;                     for (int j = 0; j < 8; ++j) sum[j] = z0[j];
;                     for (int d = 1; d < cnt; ++d) { float zd[8]; unpack8(*(const u32x4*)(zp - (size_t)d * DM), zd);
; #pragma unroll
;                         for (int j = 0; j < 8; ++j) sum[j] += zd[j]; }
;                     const float inv = 1.0f / (float)cnt;
; #pragma unroll
;                     for (int j = 0; j < 8; ++j) m[r][c][j] = sum[j] * inv - z0[j]; }
.LBB0_796:
	v_mul_hi_i32 v16, v62, s62
	v_lshrrev_b32_e32 v17, 31, v16
	v_ashrrev_i32_e32 v16, 7, v16
	v_add_u32_e32 v64, v16, v17
	v_mul_i32_i24_e32 v16, 0x810, v64
	v_ashrrev_i32_e32 v55, 31, v54
	v_sub_u32_e32 v16, v62, v16
	v_lshlrev_b64 v[14:15], 11, v[54:55]
	s_andn2_b64 vcc, exec, s[14:15]
	v_add_u32_e32 v55, 1, v16
	s_cbranch_vccnz .LBB0_802
	v_min_i32_e32 v59, v55, v1
	v_cmp_lt_i32_e32 vcc, 1, v59
	v_mov_b64_e32 v[66:67], v[68:69]
	v_mov_b64_e32 v[20:21], v[70:71]
	v_mov_b64_e32 v[18:19], v[72:73]
	v_mov_b64_e32 v[16:17], v[74:75]
	s_and_saveexec_b64 s[14:15], vcc
	s_cbranch_execz .LBB0_801
	v_lshl_add_u64 v[76:77], v[52:53], 0, v[14:15]
	v_add_u32_e32 v65, -1, v59
	s_mov_b64 s[40:41], 0
	v_mov_b64_e32 v[16:17], v[74:75]
	v_mov_b64_e32 v[18:19], v[72:73]
	v_mov_b64_e32 v[20:21], v[70:71]
	v_mov_b64_e32 v[66:67], v[68:69]
	s_mov_b64 s[40:41], exec
	global_load_dwordx4 v[174:177], v[76:77], off
	v_lshl_add_u64 v[76:77], v[76:77], 0, s[54:55]
	v_cmp_le_u32_e32 vcc, 2, v65
	s_and_b64 exec, s[40:41], vcc
	s_cbranch_execz .Lpl_c_iss
	global_load_dwordx4 v[178:181], v[76:77], off
	v_lshl_add_u64 v[76:77], v[76:77], 0, s[54:55]
	v_cmp_le_u32_e32 vcc, 3, v65
	s_and_b64 exec, s[40:41], vcc
	s_cbranch_execz .Lpl_c_iss
	global_load_dwordx4 v[182:185], v[76:77], off
.Lpl_c_iss:
	s_mov_b64 exec, s[40:41]
	s_waitcnt vmcnt(0)
	v_lshlrev_b32_e32 v234, 16, v174
	v_and_b32_e32 v235, 0xffff0000, v174
	v_pk_add_f32 v[66:67], v[66:67], v[234:235]
	v_lshlrev_b32_e32 v234, 16, v175
	v_and_b32_e32 v235, 0xffff0000, v175
	v_pk_add_f32 v[20:21], v[20:21], v[234:235]
	v_lshlrev_b32_e32 v234, 16, v176
	v_and_b32_e32 v235, 0xffff0000, v176
	v_pk_add_f32 v[18:19], v[18:19], v[234:235]
	v_lshlrev_b32_e32 v234, 16, v177
	v_and_b32_e32 v235, 0xffff0000, v177
	v_pk_add_f32 v[16:17], v[16:17], v[234:235]
	v_cmp_le_u32_e32 vcc, 2, v65
	s_and_b64 exec, s[40:41], vcc
	s_cbranch_execz .Lpl_c_done
	v_lshlrev_b32_e32 v234, 16, v178
	v_and_b32_e32 v235, 0xffff0000, v178
	v_pk_add_f32 v[66:67], v[66:67], v[234:235]
	v_lshlrev_b32_e32 v234, 16, v179
	v_and_b32_e32 v235, 0xffff0000, v179
	v_pk_add_f32 v[20:21], v[20:21], v[234:235]
	v_lshlrev_b32_e32 v234, 16, v180
	v_and_b32_e32 v235, 0xffff0000, v180
	v_pk_add_f32 v[18:19], v[18:19], v[234:235]
	v_lshlrev_b32_e32 v234, 16, v181
	v_and_b32_e32 v235, 0xffff0000, v181
	v_pk_add_f32 v[16:17], v[16:17], v[234:235]
	v_cmp_le_u32_e32 vcc, 3, v65
	s_and_b64 exec, s[40:41], vcc
	s_cbranch_execz .Lpl_c_done
	v_lshlrev_b32_e32 v234, 16, v182
	v_and_b32_e32 v235, 0xffff0000, v182
	v_pk_add_f32 v[66:67], v[66:67], v[234:235]
	v_lshlrev_b32_e32 v234, 16, v183
	v_and_b32_e32 v235, 0xffff0000, v183
	v_pk_add_f32 v[20:21], v[20:21], v[234:235]
	v_lshlrev_b32_e32 v234, 16, v184
	v_and_b32_e32 v235, 0xffff0000, v184
	v_pk_add_f32 v[18:19], v[18:19], v[234:235]
	v_lshlrev_b32_e32 v234, 16, v185
	v_and_b32_e32 v235, 0xffff0000, v185
	v_pk_add_f32 v[16:17], v[16:17], v[234:235]

; __device__ __forceinline__ void unpack8(const u32x4 w, float* v) { v[0] = bflo(w.x); v[1] = bfhi(w.x); v[2] = bflo(w.y); v[3] = bfhi(w.y); v[4] = bflo(w.z); v[5] = bfhi(w.z); v[6] = bflo(w.w); v[7] = bfhi(w.w); }
; __device__ __forceinline__ void row_res(KP kp, int gpost_in, int layer, bool has_next, int wid0, int row0, int row1, int b0, int nb, int tailp, bool pooled) {
;     ...
;                 else if (pooled) { const int t = row % LL, win = 2 << (c * 2 + (lane >> 5)), cnt = (t + 1) < win ? (t + 1) : win; const bf16* zp = MX + (size_t)row * DM + c * 512 + lane * 8;
;                     float z0[8], sum[8]; unpack8(*(const u32x4*)zp, z0);
; #pragma unroll
;                     for (int j = 0; j < 8; ++j) sum[j] = z0[j];
;                     for (int d = 1; d < cnt; ++d) { float zd[8]; unpack8(*(const u32x4*)(zp - (size_t)d * DM), zd);
; #pragma unroll
;                         for (int j = 0; j < 8; ++j) sum[j] += zd[j]; }
;                     const float inv = 1.0f / (float)cnt;
; #pragma unroll
;                     for (int j = 0; j < 8; ++j) m[r][c][j] = sum[j] * inv - z0[j]; }
.LBB0_804:
	s_andn2_b64 vcc, exec, s[14:15]
	s_cbranch_vccnz .LBB0_810
	v_min_i32_e32 v55, v55, v41
	v_cmp_lt_i32_e32 vcc, 1, v55
	v_mov_b64_e32 v[84:85], v[82:83]
	v_mov_b64_e32 v[20:21], v[80:81]
	v_mov_b64_e32 v[18:19], v[78:79]
	v_mov_b64_e32 v[16:17], v[76:77]
	s_and_saveexec_b64 s[4:5], vcc
	s_cbranch_execz .LBB0_809
	v_lshl_add_u64 v[14:15], v[56:57], 0, v[14:15]
	v_add_u32_e32 v59, -1, v55
	s_mov_b64 s[14:15], 0
	v_mov_b64_e32 v[16:17], v[76:77]
	v_mov_b64_e32 v[18:19], v[78:79]
	v_mov_b64_e32 v[20:21], v[80:81]
	v_mov_b64_e32 v[84:85], v[82:83]
	s_mov_b64 s[14:15], exec
	global_load_dwordx4 v[174:177], v[14:15], off
	v_lshl_add_u64 v[14:15], v[14:15], 0, s[54:55]
	v_cmp_le_u32_e32 vcc, 2, v59
	s_and_b64 exec, s[14:15], vcc
	s_cbranch_execz .Lpl_d_iss
	global_load_dwordx4 v[178:181], v[14:15], off
	v_lshl_add_u64 v[14:15], v[14:15], 0, s[54:55]
	v_cmp_le_u32_e32 vcc, 3, v59
	s_and_b64 exec, s[14:15], vcc
	s_cbranch_execz .Lpl_d_iss
	global_load_dwordx4 v[182:185], v[14:15], off
	v_lshl_add_u64 v[14:15], v[14:15], 0, s[54:55]
	v_cmp_le_u32_e32 vcc, 4, v59
	s_and_b64 exec, s[14:15], vcc
	s_cbranch_execz .Lpl_d_iss
	global_load_dwordx4 v[186:189], v[14:15], off
	v_lshl_add_u64 v[14:15], v[14:15], 0, s[54:55]
	v_cmp_le_u32_e32 vcc, 5, v59
	s_and_b64 exec, s[14:15], vcc
	s_cbranch_execz .Lpl_d_iss
	global_load_dwordx4 v[190:193], v[14:15], off
	v_lshl_add_u64 v[14:15], v[14:15], 0, s[54:55]
	v_cmp_le_u32_e32 vcc, 6, v59
	s_and_b64 exec, s[14:15], vcc
	s_cbranch_execz .Lpl_d_iss
	global_load_dwordx4 v[194:197], v[14:15], off
	v_lshl_add_u64 v[14:15], v[14:15], 0, s[54:55]
	v_cmp_le_u32_e32 vcc, 7, v59
	s_and_b64 exec, s[14:15], vcc
	s_cbranch_execz .Lpl_d_iss
	global_load_dwordx4 v[198:201], v[14:15], off
	v_lshl_add_u64 v[14:15], v[14:15], 0, s[54:55]
	v_cmp_le_u32_e32 vcc, 8, v59
	s_and_b64 exec, s[14:15], vcc
	s_cbranch_execz .Lpl_d_iss
	global_load_dwordx4 v[202:205], v[14:15], off
	v_lshl_add_u64 v[14:15], v[14:15], 0, s[54:55]
	v_cmp_le_u32_e32 vcc, 9, v59
	s_and_b64 exec, s[14:15], vcc
	s_cbranch_execz .Lpl_d_iss
	global_load_dwordx4 v[206:209], v[14:15], off
	v_lshl_add_u64 v[14:15], v[14:15], 0, s[54:55]
	v_cmp_le_u32_e32 vcc, 10, v59
	s_and_b64 exec, s[14:15], vcc
	s_cbranch_execz .Lpl_d_iss
	global_load_dwordx4 v[210:213], v[14:15], off
	v_lshl_add_u64 v[14:15], v[14:15], 0, s[54:55]
	v_cmp_le_u32_e32 vcc, 11, v59
	s_and_b64 exec, s[14:15], vcc
	s_cbranch_execz .Lpl_d_iss
	global_load_dwordx4 v[214:217], v[14:15], off
	v_lshl_add_u64 v[14:15], v[14:15], 0, s[54:55]
	v_cmp_le_u32_e32 vcc, 12, v59
	s_and_b64 exec, s[14:15], vcc
	s_cbranch_execz .Lpl_d_iss
	global_load_dwordx4 v[218:221], v[14:15], off
	v_lshl_add_u64 v[14:15], v[14:15], 0, s[54:55]
	v_cmp_le_u32_e32 vcc, 13, v59
	s_and_b64 exec, s[14:15], vcc
	s_cbranch_execz .Lpl_d_iss
	global_load_dwordx4 v[222:225], v[14:15], off
	v_lshl_add_u64 v[14:15], v[14:15], 0, s[54:55]
	v_cmp_le_u32_e32 vcc, 14, v59
	s_and_b64 exec, s[14:15], vcc
	s_cbranch_execz .Lpl_d_iss
	global_load_dwordx4 v[226:229], v[14:15], off
	v_lshl_add_u64 v[14:15], v[14:15], 0, s[54:55]
	v_cmp_le_u32_e32 vcc, 15, v59
	s_and_b64 exec, s[14:15], vcc
	s_cbranch_execz .Lpl_d_iss
	global_load_dwordx4 v[230:233], v[14:15], off
.Lpl_d_iss:
	s_mov_b64 exec, s[14:15]
	s_waitcnt vmcnt(0)
	v_lshlrev_b32_e32 v234, 16, v174
	v_and_b32_e32 v235, 0xffff0000, v174
	v_pk_add_f32 v[84:85], v[84:85], v[234:235]
	v_lshlrev_b32_e32 v234, 16, v175
	v_and_b32_e32 v235, 0xffff0000, v175
	v_pk_add_f32 v[20:21], v[20:21], v[234:235]
	v_lshlrev_b32_e32 v234, 16, v176
	v_and_b32_e32 v235, 0xffff0000, v176
	v_pk_add_f32 v[18:19], v[18:19], v[234:235]
	v_lshlrev_b32_e32 v234, 16, v177
	v_and_b32_e32 v235, 0xffff0000, v177
	v_pk_add_f32 v[16:17], v[16:17], v[234:235]
	v_cmp_le_u32_e32 vcc, 2, v59
	s_and_b64 exec, s[14:15], vcc
	s_cbranch_execz .Lpl_d_done
	v_lshlrev_b32_e32 v234, 16, v178
	v_and_b32_e32 v235, 0xffff0000, v178
	v_pk_add_f32 v[84:85], v[84:85], v[234:235]
	v_lshlrev_b32_e32 v234, 16, v179
	v_and_b32_e32 v235, 0xffff0000, v179
	v_pk_add_f32 v[20:21], v[20:21], v[234:235]
	v_lshlrev_b32_e32 v234, 16, v180
	v_and_b32_e32 v235, 0xffff0000, v180
	v_pk_add_f32 v[18:19], v[18:19], v[234:235]
	v_lshlrev_b32_e32 v234, 16, v181
	v_and_b32_e32 v235, 0xffff0000, v181
	v_pk_add_f32 v[16:17], v[16:17], v[234:235]
	v_cmp_le_u32_e32 vcc, 3, v59
	s_and_b64 exec, s[14:15], vcc
	s_cbranch_execz .Lpl_d_done
	v_lshlrev_b32_e32 v234, 16, v182
	v_and_b32_e32 v235, 0xffff0000, v182
	v_pk_add_f32 v[84:85], v[84:85], v[234:235]
	v_lshlrev_b32_e32 v234, 16, v183
	v_and_b32_e32 v235, 0xffff0000, v183
	v_pk_add_f32 v[20:21], v[20:21], v[234:235]
	v_lshlrev_b32_e32 v234, 16, v184
	v_and_b32_e32 v235, 0xffff0000, v184
	v_pk_add_f32 v[18:19], v[18:19], v[234:235]
	v_lshlrev_b32_e32 v234, 16, v185
	v_and_b32_e32 v235, 0xffff0000, v185
	v_pk_add_f32 v[16:17], v[16:17], v[234:235]
	v_cmp_le_u32_e32 vcc, 4, v59
	s_and_b64 exec, s[14:15], vcc
	s_cbranch_execz .Lpl_d_done
	v_lshlrev_b32_e32 v234, 16, v186
	v_and_b32_e32 v235, 0xffff0000, v186
	v_pk_add_f32 v[84:85], v[84:85], v[234:235]
	v_lshlrev_b32_e32 v234, 16, v187
	v_and_b32_e32 v235, 0xffff0000, v187
	v_pk_add_f32 v[20:21], v[20:21], v[234:235]
	v_lshlrev_b32_e32 v234, 16, v188
	v_and_b32_e32 v235, 0xffff0000, v188
	v_pk_add_f32 v[18:19], v[18:19], v[234:235]
	v_lshlrev_b32_e32 v234, 16, v189
	v_and_b32_e32 v235, 0xffff0000, v189
	v_pk_add_f32 v[16:17], v[16:17], v[234:235]
	v_cmp_le_u32_e32 vcc, 5, v59
	s_and_b64 exec, s[14:15], vcc
	s_cbranch_execz .Lpl_d_done
; __device__ __forceinline__ void unpack8(const u32x4 w, float* v) { v[0] = bflo(w.x); v[1] = bfhi(w.x); v[2] = bflo(w.y); v[3] = bfhi(w.y); v[4] = bflo(w.z); v[5] = bfhi(w.z); v[6] = bflo(w.w); v[7] = bfhi(w.w); }
; __device__ __forceinline__ void row_res(KP kp, int gpost_in, int layer, bool has_next, int wid0, int row0, int row1, int b0, int nb, int tailp, bool pooled) {
;     ...
;                 else if (pooled) { const int t = row % LL, win = 2 << (c * 2 + (lane >> 5)), cnt = (t + 1) < win ? (t + 1) : win; const bf16* zp = MX + (size_t)row * DM + c * 512 + lane * 8;
;                     float z0[8], sum[8]; unpack8(*(const u32x4*)zp, z0);
; #pragma unroll
;                     for (int j = 0; j < 8; ++j) sum[j] = z0[j];
;                     for (int d = 1; d < cnt; ++d) { float zd[8]; unpack8(*(const u32x4*)(zp - (size_t)d * DM), zd);
; #pragma unroll
;                         for (int j = 0; j < 8; ++j) sum[j] += zd[j]; }
;                     const float inv = 1.0f / (float)cnt;
; #pragma unroll
;                     for (int j = 0; j < 8; ++j) m[r][c][j] = sum[j] * inv - z0[j]; }
	v_lshlrev_b32_e32 v234, 16, v190
	v_and_b32_e32 v235, 0xffff0000, v190
	v_pk_add_f32 v[84:85], v[84:85], v[234:235]
	v_lshlrev_b32_e32 v234, 16, v191
	v_and_b32_e32 v235, 0xffff0000, v191
	v_pk_add_f32 v[20:21], v[20:21], v[234:235]
	v_lshlrev_b32_e32 v234, 16, v192
	v_and_b32_e32 v235, 0xffff0000, v192
	v_pk_add_f32 v[18:19], v[18:19], v[234:235]
	v_lshlrev_b32_e32 v234, 16, v193
	v_and_b32_e32 v235, 0xffff0000, v193
	v_pk_add_f32 v[16:17], v[16:17], v[234:235]
	v_cmp_le_u32_e32 vcc, 6, v59
	s_and_b64 exec, s[14:15], vcc
	s_cbranch_execz .Lpl_d_done
	v_lshlrev_b32_e32 v234, 16, v194
	v_and_b32_e32 v235, 0xffff0000, v194
	v_pk_add_f32 v[84:85], v[84:85], v[234:235]
	v_lshlrev_b32_e32 v234, 16, v195
	v_and_b32_e32 v235, 0xffff0000, v195
	v_pk_add_f32 v[20:21], v[20:21], v[234:235]
	v_lshlrev_b32_e32 v234, 16, v196
	v_and_b32_e32 v235, 0xffff0000, v196
	v_pk_add_f32 v[18:19], v[18:19], v[234:235]
	v_lshlrev_b32_e32 v234, 16, v197
	v_and_b32_e32 v235, 0xffff0000, v197
	v_pk_add_f32 v[16:17], v[16:17], v[234:235]
	v_cmp_le_u32_e32 vcc, 7, v59
	s_and_b64 exec, s[14:15], vcc
	s_cbranch_execz .Lpl_d_done
	v_lshlrev_b32_e32 v234, 16, v198
	v_and_b32_e32 v235, 0xffff0000, v198
	v_pk_add_f32 v[84:85], v[84:85], v[234:235]
	v_lshlrev_b32_e32 v234, 16, v199
	v_and_b32_e32 v235, 0xffff0000, v199
	v_pk_add_f32 v[20:21], v[20:21], v[234:235]
	v_lshlrev_b32_e32 v234, 16, v200
	v_and_b32_e32 v235, 0xffff0000, v200
	v_pk_add_f32 v[18:19], v[18:19], v[234:235]
	v_lshlrev_b32_e32 v234, 16, v201
	v_and_b32_e32 v235, 0xffff0000, v201
	v_pk_add_f32 v[16:17], v[16:17], v[234:235]
	v_cmp_le_u32_e32 vcc, 8, v59
	s_and_b64 exec, s[14:15], vcc
	s_cbranch_execz .Lpl_d_done
	v_lshlrev_b32_e32 v234, 16, v202
	v_and_b32_e32 v235, 0xffff0000, v202
	v_pk_add_f32 v[84:85], v[84:85], v[234:235]
	v_lshlrev_b32_e32 v234, 16, v203
	v_and_b32_e32 v235, 0xffff0000, v203
	v_pk_add_f32 v[20:21], v[20:21], v[234:235]
	v_lshlrev_b32_e32 v234, 16, v204
	v_and_b32_e32 v235, 0xffff0000, v204
	v_pk_add_f32 v[18:19], v[18:19], v[234:235]
	v_lshlrev_b32_e32 v234, 16, v205
	v_and_b32_e32 v235, 0xffff0000, v205
	v_pk_add_f32 v[16:17], v[16:17], v[234:235]
	v_cmp_le_u32_e32 vcc, 9, v59
	s_and_b64 exec, s[14:15], vcc
	s_cbranch_execz .Lpl_d_done
	v_lshlrev_b32_e32 v234, 16, v206
	v_and_b32_e32 v235, 0xffff0000, v206
	v_pk_add_f32 v[84:85], v[84:85], v[234:235]
	v_lshlrev_b32_e32 v234, 16, v207
	v_and_b32_e32 v235, 0xffff0000, v207
	v_pk_add_f32 v[20:21], v[20:21], v[234:235]
	v_lshlrev_b32_e32 v234, 16, v208
	v_and_b32_e32 v235, 0xffff0000, v208
	v_pk_add_f32 v[18:19], v[18:19], v[234:235]
	v_lshlrev_b32_e32 v234, 16, v209
	v_and_b32_e32 v235, 0xffff0000, v209
	v_pk_add_f32 v[16:17], v[16:17], v[234:235]
	v_cmp_le_u32_e32 vcc, 10, v59
	s_and_b64 exec, s[14:15], vcc
	s_cbranch_execz .Lpl_d_done
	v_lshlrev_b32_e32 v234, 16, v210
	v_and_b32_e32 v235, 0xffff0000, v210
	v_pk_add_f32 v[84:85], v[84:85], v[234:235]
	v_lshlrev_b32_e32 v234, 16, v211
	v_and_b32_e32 v235, 0xffff0000, v211
	v_pk_add_f32 v[20:21], v[20:21], v[234:235]
	v_lshlrev_b32_e32 v234, 16, v212
	v_and_b32_e32 v235, 0xffff0000, v212
	v_pk_add_f32 v[18:19], v[18:19], v[234:235]
	v_lshlrev_b32_e32 v234, 16, v213
	v_and_b32_e32 v235, 0xffff0000, v213
	v_pk_add_f32 v[16:17], v[16:17], v[234:235]
	v_cmp_le_u32_e32 vcc, 11, v59
	s_and_b64 exec, s[14:15], vcc
	s_cbranch_execz .Lpl_d_done
	v_lshlrev_b32_e32 v234, 16, v214
	v_and_b32_e32 v235, 0xffff0000, v214
	v_pk_add_f32 v[84:85], v[84:85], v[234:235]
	v_lshlrev_b32_e32 v234, 16, v215
	v_and_b32_e32 v235, 0xffff0000, v215
	v_pk_add_f32 v[20:21], v[20:21], v[234:235]
	v_lshlrev_b32_e32 v234, 16, v216
	v_and_b32_e32 v235, 0xffff0000, v216
	v_pk_add_f32 v[18:19], v[18:19], v[234:235]
	v_lshlrev_b32_e32 v234, 16, v217
	v_and_b32_e32 v235, 0xffff0000, v217
	v_pk_add_f32 v[16:17], v[16:17], v[234:235]
	v_cmp_le_u32_e32 vcc, 12, v59
	s_and_b64 exec, s[14:15], vcc
	s_cbranch_execz .Lpl_d_done
	v_lshlrev_b32_e32 v234, 16, v218
	v_and_b32_e32 v235, 0xffff0000, v218
	v_pk_add_f32 v[84:85], v[84:85], v[234:235]
	v_lshlrev_b32_e32 v234, 16, v219
	v_and_b32_e32 v235, 0xffff0000, v219
	v_pk_add_f32 v[20:21], v[20:21], v[234:235]
	v_lshlrev_b32_e32 v234, 16, v220
	v_and_b32_e32 v235, 0xffff0000, v220
	v_pk_add_f32 v[18:19], v[18:19], v[234:235]
	v_lshlrev_b32_e32 v234, 16, v221
	v_and_b32_e32 v235, 0xffff0000, v221
	v_pk_add_f32 v[16:17], v[16:17], v[234:235]
	v_cmp_le_u32_e32 vcc, 13, v59
	s_and_b64 exec, s[14:15], vcc
	s_cbranch_execz .Lpl_d_done
	v_lshlrev_b32_e32 v234, 16, v222
	v_and_b32_e32 v235, 0xffff0000, v222
	v_pk_add_f32 v[84:85], v[84:85], v[234:235]
	v_lshlrev_b32_e32 v234, 16, v223
	v_and_b32_e32 v235, 0xffff0000, v223
	v_pk_add_f32 v[20:21], v[20:21], v[234:235]
	v_lshlrev_b32_e32 v234, 16, v224
	v_and_b32_e32 v235, 0xffff0000, v224
	v_pk_add_f32 v[18:19], v[18:19], v[234:235]
	v_lshlrev_b32_e32 v234, 16, v225
	v_and_b32_e32 v235, 0xffff0000, v225
	v_pk_add_f32 v[16:17], v[16:17], v[234:235]
	v_cmp_le_u32_e32 vcc, 14, v59
	s_and_b64 exec, s[14:15], vcc
	s_cbranch_execz .Lpl_d_done
	v_lshlrev_b32_e32 v234, 16, v226
	v_and_b32_e32 v235, 0xffff0000, v226
	v_pk_add_f32 v[84:85], v[84:85], v[234:235]
	v_lshlrev_b32_e32 v234, 16, v227
	v_and_b32_e32 v235, 0xffff0000, v227
	v_pk_add_f32 v[20:21], v[20:21], v[234:235]
	v_lshlrev_b32_e32 v234, 16, v228
	v_and_b32_e32 v235, 0xffff0000, v228
	v_pk_add_f32 v[18:19], v[18:19], v[234:235]
	v_lshlrev_b32_e32 v234, 16, v229
	v_and_b32_e32 v235, 0xffff0000, v229
	v_pk_add_f32 v[16:17], v[16:17], v[234:235]
	v_cmp_le_u32_e32 vcc, 15, v59
	s_and_b64 exec, s[14:15], vcc
	s_cbranch_execz .Lpl_d_done
	v_lshlrev_b32_e32 v234, 16, v230
	v_and_b32_e32 v235, 0xffff0000, v230
	v_pk_add_f32 v[84:85], v[84:85], v[234:235]
	v_lshlrev_b32_e32 v234, 16, v231
	v_and_b32_e32 v235, 0xffff0000, v231
	v_pk_add_f32 v[20:21], v[20:21], v[234:235]
	v_lshlrev_b32_e32 v234, 16, v232
	v_and_b32_e32 v235, 0xffff0000, v232
	v_pk_add_f32 v[18:19], v[18:19], v[234:235]
	v_lshlrev_b32_e32 v234, 16, v233
	v_and_b32_e32 v235, 0xffff0000, v233
	v_pk_add_f32 v[16:17], v[16:17], v[234:235]
